# attention item prologue de-serialised: first K/V tile LDS-DMAs issued right after the Q loads, ahead of the Q-dependent norm bound
# baseline (speedup 1.0000x reference)
.LBB0_840:
	s_or_b64 exec, exec, s[0:1]
	v_add_u32_e32 v136, v6, v150
	v_min_i32_e32 v112, 0x807f, v136
	v_lshlrev_b64 v[6:7], 11, v[112:113]
	v_lshl_add_u64 v[6:7], s[16:17], 0, v[6:7]
	v_lshl_add_u64 v[6:7], v[138:139], 1, v[6:7]
	v_mov_b32_e32 v125, v113
	v_lshl_add_u64 v[6:7], v[6:7], 0, v[124:125]
	v_lshlrev_b32_e32 v112, 1, v114
	v_lshl_add_u64 v[6:7], v[6:7], 0, v[112:113]
	global_load_dwordx4 v[96:99], v[6:7], off
	global_load_dwordx4 v[100:103], v[6:7], off offset:32
	global_load_dwordx4 v[104:107], v[6:7], off offset:64
	global_load_dwordx4 v[108:111], v[6:7], off offset:96
	v_readfirstlane_b32 s98, v0
	v_readfirstlane_b32 s99, v1
	v_readfirstlane_b32 s100, v2
	v_readfirstlane_b32 s101, v3
	v_mov_b32_e32 v129, v113
	v_mul_u32_u24_e32 v5, v4, v151
	v_lshl_add_u64 v[6:7], v[0:1], 0, v[128:129]
	v_mov_b32_e32 v131, v113
	v_lshlrev_b32_e32 v8, 1, v5
	v_mov_b32_e32 v9, v113
	v_readfirstlane_b32 s0, v155
	v_add_u32_e32 v5, 0x4000, v155
	v_lshl_add_u64 v[6:7], v[6:7], 0, v[130:131]
	v_lshl_add_u64 v[10:11], v[2:3], 0, v[8:9]
	v_mov_b32_e32 v133, v113
	s_mov_b32 m0, s0
	v_readfirstlane_b32 s0, v5
	v_add_u32_e32 v5, 0x1000, v155
	v_lshl_add_u64 v[10:11], v[10:11], 0, v[132:133]
	global_load_lds_dwordx4 v[6:7], off
	s_mov_b32 m0, s0
	v_readfirstlane_b32 s0, v5
	v_add_u32_e32 v5, 0x5000, v155
	global_load_lds_dwordx4 v[10:11], off
	v_lshl_add_u64 v[12:13], v[6:7], 0, s[34:35]
	s_mov_b32 m0, s0
	v_lshlrev_b32_e32 v112, 6, v4
	v_readfirstlane_b32 s0, v5
	v_add_u32_e32 v5, 0x2000, v155
	global_load_lds_dwordx4 v[12:13], off
	v_lshl_add_u64 v[10:11], v[10:11], 0, v[112:113]
	s_mov_b32 m0, s0
	v_readfirstlane_b32 s0, v5
	v_add_u32_e32 v5, 0x6000, v155
	global_load_lds_dwordx4 v[10:11], off
	v_lshl_add_u64 v[12:13], v[6:7], 0, s[36:37]
	s_mov_b32 m0, s0
	v_readfirstlane_b32 s0, v5
	v_add_u32_e32 v5, 0x3000, v155
	global_load_lds_dwordx4 v[12:13], off
	v_lshl_add_u64 v[10:11], v[10:11], 0, v[112:113]
	s_mov_b32 m0, s0
	v_readfirstlane_b32 s0, v5
	v_add_u32_e32 v5, 0x7000, v155
	global_load_lds_dwordx4 v[10:11], off
	v_lshl_add_u64 v[6:7], v[6:7], 0, s[38:39]
	s_mov_b32 m0, s0
	v_readfirstlane_b32 s0, v5
	global_load_lds_dwordx4 v[6:7], off
	v_lshl_add_u64 v[6:7], v[10:11], 0, v[112:113]
	s_mov_b32 m0, s0
	v_lshl_add_u64 v[140:141], v[0:1], 0, v[120:121]
	global_load_lds_dwordx4 v[6:7], off
	v_lshl_add_u64 v[0:1], v[2:3], 0, v[122:123]
	v_mov_b32_e32 v14, v113
	v_mov_b32_e32 v15, v113
	v_lshl_add_u64 v[142:143], v[0:1], 0, v[8:9]
	v_lshlrev_b32_e32 v146, 7, v4
	v_mul_hi_u32_u24_e32 v149, 0xc0, v4
	v_mul_u32_u24_e32 v148, 0xc0, v4
	v_mov_b32_e32 v172, 0
	s_mov_b64 s[44:45], 0
	s_mov_b64 s[8:9], 0
	v_mov_b32_e32 v125, 0
	s_and_saveexec_b64 s[0:1], vcc
	s_cbranch_execz .LBB0_842
	s_waitcnt vmcnt(11)
	v_and_b32_e32 v6, 0xffff0000, v96
	v_lshlrev_b32_e32 v5, 16, v96
	v_mul_f32_e32 v8, v6, v6
	v_fmac_f32_e32 v8, v5, v5
	v_lshlrev_b32_e32 v5, 16, v97
	v_fmac_f32_e32 v8, v5, v5
	v_and_b32_e32 v5, 0xffff0000, v97
	v_fmac_f32_e32 v8, v5, v5
	v_lshlrev_b32_e32 v5, 16, v98
	v_fmac_f32_e32 v8, v5, v5
	v_and_b32_e32 v5, 0xffff0000, v98
	v_fmac_f32_e32 v8, v5, v5
	v_lshlrev_b32_e32 v5, 16, v99
	v_fmac_f32_e32 v8, v5, v5
	v_and_b32_e32 v5, 0xffff0000, v99
	v_fmac_f32_e32 v8, v5, v5
	s_waitcnt vmcnt(10)
	v_lshlrev_b32_e32 v5, 16, v100
	v_fmac_f32_e32 v8, v5, v5
	v_and_b32_e32 v5, 0xffff0000, v100
	v_fmac_f32_e32 v8, v5, v5
	v_lshlrev_b32_e32 v5, 16, v101
	v_fmac_f32_e32 v8, v5, v5
	v_and_b32_e32 v5, 0xffff0000, v101
	v_fmac_f32_e32 v8, v5, v5
	v_lshlrev_b32_e32 v5, 16, v102
	v_fmac_f32_e32 v8, v5, v5
	v_and_b32_e32 v5, 0xffff0000, v102
	v_fmac_f32_e32 v8, v5, v5
	v_lshlrev_b32_e32 v5, 16, v103
	v_fmac_f32_e32 v8, v5, v5
	v_and_b32_e32 v5, 0xffff0000, v103
	v_fmac_f32_e32 v8, v5, v5
	s_waitcnt vmcnt(9)
	v_lshlrev_b32_e32 v5, 16, v104
	v_fmac_f32_e32 v8, v5, v5
	v_and_b32_e32 v5, 0xffff0000, v104
	v_fmac_f32_e32 v8, v5, v5
	v_lshlrev_b32_e32 v5, 16, v105
	v_fmac_f32_e32 v8, v5, v5
	v_and_b32_e32 v5, 0xffff0000, v105
	v_fmac_f32_e32 v8, v5, v5
	v_lshlrev_b32_e32 v5, 16, v106
	v_fmac_f32_e32 v8, v5, v5
	v_and_b32_e32 v5, 0xffff0000, v106
	v_fmac_f32_e32 v8, v5, v5
	v_lshlrev_b32_e32 v5, 16, v107
	v_fmac_f32_e32 v8, v5, v5
	v_and_b32_e32 v5, 0xffff0000, v107
	s_waitcnt vmcnt(8)
	v_and_b32_e32 v7, 0xffff0000, v108
	v_lshlrev_b32_e32 v6, 16, v108
	v_fmac_f32_e32 v8, v5, v5
	v_pk_mul_f32 v[6:7], v[6:7], v[6:7]
	s_nop 0
	v_add_f32_e32 v5, v6, v8
	v_add_f32_e32 v5, v7, v5
	v_and_b32_e32 v7, 0xffff0000, v109
	v_lshlrev_b32_e32 v6, 16, v109
	v_pk_mul_f32 v[6:7], v[6:7], v[6:7]
	s_nop 0
	v_add_f32_e32 v5, v6, v5
	v_add_f32_e32 v5, v7, v5
	v_and_b32_e32 v7, 0xffff0000, v110
	v_lshlrev_b32_e32 v6, 16, v110
	v_pk_mul_f32 v[6:7], v[6:7], v[6:7]
	s_nop 0
	v_add_f32_e32 v5, v6, v5
	v_add_f32_e32 v5, v7, v5
	v_and_b32_e32 v7, 0xffff0000, v111
	v_lshlrev_b32_e32 v6, 16, v111
	v_pk_mul_f32 v[6:7], v[6:7], v[6:7]
	s_nop 0
	v_add_f32_e32 v5, v6, v5
	v_add_f32_e32 v5, v7, v5
	ds_bpermute_b32 v6, v115, v5
	s_waitcnt lgkmcnt(0)
	v_add_f32_e32 v5, v5, v6
	v_sqrt_f32_e32 v5, v5
	s_nop 0
	v_fmaak_f32 v5, v165, v5, 0x3d4ccccd
	v_cmp_lt_f32_e32 vcc, s55, v5
	s_cmp_eq_u64 vcc, 0
	s_cselect_b64 vcc, -1, 0
	v_cndmask_b32_e32 v125, 0, v5, vcc
	s_and_b64 s[8:9], vcc, exec
.LBB0_842:
	s_or_b64 exec, exec, s[0:1]
	v_mov_b32_e32 v0, v113
	v_mov_b32_e32 v1, v113
	v_mov_b32_e32 v2, v113
	v_mov_b32_e32 v3, v113
	v_mov_b32_e32 v4, v113
	v_mov_b32_e32 v5, v113
	v_mov_b32_e32 v6, v113
	v_mov_b32_e32 v7, v113
	v_mov_b32_e32 v8, v113
	v_mov_b32_e32 v10, v113
	v_mov_b32_e32 v11, v113
	v_mov_b32_e32 v12, v113
	v_mov_b32_e32 v13, v113
	v_mov_b64_e32 v[30:31], v[14:15]
	v_mov_b64_e32 v[46:47], v[14:15]
	v_mov_b64_e32 v[62:63], v[14:15]
	s_xor_b64 s[46:47], s[8:9], -1
	v_cmp_lt_u32_e64 s[8:9], v145, v127
	v_cmp_ge_u32_e64 s[10:11], v145, v127
	s_mov_b32 s33, 1
	v_mov_b32_e32 v147, v113
	v_lshlrev_b32_e32 v129, 6, v137
	v_mov_b64_e32 v[28:29], v[12:13]
	v_mov_b64_e32 v[26:27], v[10:11]
	v_mov_b64_e32 v[24:25], v[8:9]
	v_mov_b64_e32 v[22:23], v[6:7]
	v_mov_b64_e32 v[20:21], v[4:5]
	v_mov_b64_e32 v[18:19], v[2:3]
	v_mov_b64_e32 v[16:17], v[0:1]
	v_mov_b64_e32 v[44:45], v[12:13]
	v_mov_b64_e32 v[42:43], v[10:11]
	v_mov_b64_e32 v[40:41], v[8:9]
	v_mov_b64_e32 v[38:39], v[6:7]
	v_mov_b64_e32 v[36:37], v[4:5]
	v_mov_b64_e32 v[34:35], v[2:3]
	v_mov_b64_e32 v[32:33], v[0:1]
	v_mov_b64_e32 v[60:61], v[12:13]
	v_mov_b64_e32 v[58:59], v[10:11]
	v_mov_b64_e32 v[56:57], v[8:9]
	v_mov_b64_e32 v[54:55], v[6:7]
	v_mov_b64_e32 v[52:53], v[4:5]
	v_mov_b64_e32 v[50:51], v[2:3]
	v_mov_b64_e32 v[48:49], v[0:1]
	v_mov_b32_e32 v131, 0
	s_waitcnt vmcnt(0)
	v_subrev_u32_e32 v200, s98, v140
	v_subrev_u32_e32 v204, s100, v142
	v_add_u32_e32 v201, s34, v200
	v_add_u32_e32 v202, s36, v200
	v_add_u32_e32 v203, s38, v200
	v_add_u32_e32 v205, v204, v112
	v_add_u32_e32 v206, v204, v146
	v_add_u32_e32 v207, v204, v148
	v_readfirstlane_b32 s60, v155
	v_xor_b32_e32 v232, 0x80000000, v125
	v_mov_b32_e32 v233, v232
	v_mov_b32_e32 v234, v232
	v_mov_b32_e32 v235, v232
	v_mov_b32_e32 v236, v232
	v_mov_b32_e32 v237, v232
	v_mov_b32_e32 v238, v232
	v_mov_b32_e32 v239, v232
	v_mov_b32_e32 v240, v232
	v_mov_b32_e32 v241, v232
	v_mov_b32_e32 v242, v232
	v_mov_b32_e32 v243, v232
	v_mov_b32_e32 v244, v232
	v_mov_b32_e32 v245, v232
	v_mov_b32_e32 v246, v232
	v_mov_b32_e32 v247, v232
	s_branch .LBB0_845
